# P0: prefetch 5 cache-conversion items at entry, store at phase end; rebalance weight-conv items
# speedup vs baseline: 1.0040x; 1.0040x over previous
_Z11mega_kernelILb1EEv6Paramsii:
	s_load_dwordx2 s[100:101], s[0:1], 0x198
	s_load_dword s3, s[0:1], 0x228
	s_load_dwordx2 s[4:5], s[0:1], 0x68
	s_load_dwordx2 s[6:7], s[0:1], 0xb0
	s_load_dwordx2 s[8:9], s[0:1], 0xb8
	s_load_dwordx2 s[10:11], s[0:1], 0xd8
	s_load_dwordx8 s[24:31], s[0:1], 0x18
	v_and_b32_e32 v1, 0x3ff, v0
	v_lshrrev_b32_e32 v2, 6, v1
	v_and_b32_e32 v3, 63, v1
	v_lshlrev_b32_e32 v2, 12, v2
	v_lshl_or_b32 v2, v3, 4, v2
	v_and_b32_e32 v3, 31, v1
	v_lshrrev_b32_e32 v4, 5, v1
	v_lshlrev_b32_e32 v3, 4, v3
	s_waitcnt lgkmcnt(0)
	s_cmp_eq_u32 s3, 0x200
	s_cselect_b32 s20, 1, 0
	v_writelane_b32 v255, s20, 46
	s_cbranch_scc0 .Lcc_skip
	s_movk_i32 s20, 0x200
	s_cmpk_lt_u32 s2, 0x180
	s_cselect_b32 s20, 0x400, s20
	s_add_u32 s20, s20, s2
	s_sub_u32 s21, s20, 0x380
	s_lshl_b32 s21, s21, 8
	v_add_u32_e32 v6, s21, v1
	s_cmpk_lt_u32 s20, 0x480
	s_cbranch_scc1 .LccA0
	s_cmpk_lt_u32 s20, 0x580
	s_cbranch_scc1 .LccB0
	s_cmpk_lt_u32 s20, 0x980
	s_cbranch_scc1 .LccC0
	v_add_u32_e32 v6, 0xfffa0000, v6
	v_and_b32_e32 v7, 0xff, v6
	v_bfe_u32 v8, v6, 8, 7
	v_bfe_u32 v9, v6, 15, 2
	v_lshl_or_b32 v8, v7, 9, v8
	v_lshl_or_b32 v8, v9, 7, v8
	v_and_b32_e32 v10, 0xfffe0000, v6
	v_or_b32_e32 v8, v8, v10
	v_lshlrev_b32_e32 v8, 2, v8
	global_load_dword v130, v8, s[30:31]
	s_branch .LccE0
.LccC0:
	v_add_u32_e32 v6, 0xfffe0000, v6
	v_and_b32_e32 v7, 0x7f, v6
	v_bfe_u32 v8, v6, 7, 8
	v_bfe_u32 v9, v6, 15, 2
	v_lshl_or_b32 v7, v8, 9, v7
	v_lshl_or_b32 v7, v9, 7, v7
	v_and_b32_e32 v10, 0xfffe0000, v6
	v_or_b32_e32 v8, v7, v10
	v_lshlrev_b32_e32 v8, 2, v8
	global_load_dword v130, v8, s[28:29]
	s_branch .LccE0
.LccB0:
	v_add_u32_e32 v6, 0xffff0000, v6
	v_and_b32_e32 v7, 0xff, v6
	v_bfe_u32 v8, v6, 8, 6
	v_bfe_u32 v9, v6, 14, 1
	v_lshl_or_b32 v8, v7, 7, v8
	v_lshl_or_b32 v8, v9, 6, v8
	v_and_b32_e32 v10, 0xffff8000, v6
	v_or_b32_e32 v8, v8, v10
	v_lshlrev_b32_e32 v8, 2, v8
	global_load_dword v130, v8, s[26:27]
	s_branch .LccE0
.LccA0:
	v_and_b32_e32 v7, 63, v6
	v_bfe_u32 v8, v6, 6, 8
	v_bfe_u32 v9, v6, 14, 1
	v_lshl_or_b32 v7, v8, 7, v7
	v_lshl_or_b32 v7, v9, 6, v7
	v_and_b32_e32 v10, 0xffff8000, v6
	v_or_b32_e32 v8, v7, v10
	v_lshlrev_b32_e32 v8, 2, v8
	global_load_dword v130, v8, s[24:25]
.LccE0:
	v_lshlrev_b32_e32 v135, 1, v6
	s_add_u32 s20, s20, 0x200
	s_sub_u32 s21, s20, 0x380
	s_lshl_b32 s21, s21, 8
	v_add_u32_e32 v6, s21, v1
	s_cmpk_lt_u32 s20, 0x480
	s_cbranch_scc1 .LccA1
	s_cmpk_lt_u32 s20, 0x580
	s_cbranch_scc1 .LccB1
	s_cmpk_lt_u32 s20, 0x980
	s_cbranch_scc1 .LccC1
	v_add_u32_e32 v6, 0xfffa0000, v6
	v_and_b32_e32 v7, 0xff, v6
	v_bfe_u32 v8, v6, 8, 7
	v_bfe_u32 v9, v6, 15, 2
	v_lshl_or_b32 v8, v7, 9, v8
	v_lshl_or_b32 v8, v9, 7, v8
	v_and_b32_e32 v10, 0xfffe0000, v6
	v_or_b32_e32 v8, v8, v10
	v_lshlrev_b32_e32 v8, 2, v8
	global_load_dword v131, v8, s[30:31]
	s_branch .LccE1
.LccC1:
	v_add_u32_e32 v6, 0xfffe0000, v6
	v_and_b32_e32 v7, 0x7f, v6
	v_bfe_u32 v8, v6, 7, 8
	v_bfe_u32 v9, v6, 15, 2
	v_lshl_or_b32 v7, v8, 9, v7
	v_lshl_or_b32 v7, v9, 7, v7
	v_and_b32_e32 v10, 0xfffe0000, v6
	v_or_b32_e32 v8, v7, v10
	v_lshlrev_b32_e32 v8, 2, v8
	global_load_dword v131, v8, s[28:29]
	s_branch .LccE1
.LccB1:
	v_add_u32_e32 v6, 0xffff0000, v6
	v_and_b32_e32 v7, 0xff, v6
	v_bfe_u32 v8, v6, 8, 6
	v_bfe_u32 v9, v6, 14, 1
	v_lshl_or_b32 v8, v7, 7, v8
	v_lshl_or_b32 v8, v9, 6, v8
	v_and_b32_e32 v10, 0xffff8000, v6
	v_or_b32_e32 v8, v8, v10
	v_lshlrev_b32_e32 v8, 2, v8
	global_load_dword v131, v8, s[26:27]
	s_branch .LccE1
.LccA1:
	v_and_b32_e32 v7, 63, v6
	v_bfe_u32 v8, v6, 6, 8
	v_bfe_u32 v9, v6, 14, 1
	v_lshl_or_b32 v7, v8, 7, v7
	v_lshl_or_b32 v7, v9, 6, v7
	v_and_b32_e32 v10, 0xffff8000, v6
	v_or_b32_e32 v8, v7, v10
	v_lshlrev_b32_e32 v8, 2, v8
	global_load_dword v131, v8, s[24:25]
.LccE1:
	v_lshlrev_b32_e32 v136, 1, v6
	s_add_u32 s20, s20, 0x200
	s_sub_u32 s21, s20, 0x380
	s_lshl_b32 s21, s21, 8
	v_add_u32_e32 v6, s21, v1
	s_cmpk_lt_u32 s20, 0x480
	s_cbranch_scc1 .LccA2
	s_cmpk_lt_u32 s20, 0x580
	s_cbranch_scc1 .LccB2
	s_cmpk_lt_u32 s20, 0x980
	s_cbranch_scc1 .LccC2
	v_add_u32_e32 v6, 0xfffa0000, v6
	v_and_b32_e32 v7, 0xff, v6
	v_bfe_u32 v8, v6, 8, 7
	v_bfe_u32 v9, v6, 15, 2
	v_lshl_or_b32 v8, v7, 9, v8
	v_lshl_or_b32 v8, v9, 7, v8
	v_and_b32_e32 v10, 0xfffe0000, v6
	v_or_b32_e32 v8, v8, v10
	v_lshlrev_b32_e32 v8, 2, v8
	global_load_dword v132, v8, s[30:31]
	s_branch .LccE2
.LccC2:
	v_add_u32_e32 v6, 0xfffe0000, v6
	v_and_b32_e32 v7, 0x7f, v6
	v_bfe_u32 v8, v6, 7, 8
	v_bfe_u32 v9, v6, 15, 2
	v_lshl_or_b32 v7, v8, 9, v7
	v_lshl_or_b32 v7, v9, 7, v7
	v_and_b32_e32 v10, 0xfffe0000, v6
	v_or_b32_e32 v8, v7, v10
	v_lshlrev_b32_e32 v8, 2, v8
	global_load_dword v132, v8, s[28:29]
	s_branch .LccE2
.LccB2:
	v_add_u32_e32 v6, 0xffff0000, v6
	v_and_b32_e32 v7, 0xff, v6
	v_bfe_u32 v8, v6, 8, 6
	v_bfe_u32 v9, v6, 14, 1
	v_lshl_or_b32 v8, v7, 7, v8
	v_lshl_or_b32 v8, v9, 6, v8
	v_and_b32_e32 v10, 0xffff8000, v6
	v_or_b32_e32 v8, v8, v10
	v_lshlrev_b32_e32 v8, 2, v8
	global_load_dword v132, v8, s[26:27]
	s_branch .LccE2
.LccA2:
	v_and_b32_e32 v7, 63, v6
	v_bfe_u32 v8, v6, 6, 8
	v_bfe_u32 v9, v6, 14, 1
	v_lshl_or_b32 v7, v8, 7, v7
	v_lshl_or_b32 v7, v9, 6, v7
	v_and_b32_e32 v10, 0xffff8000, v6
	v_or_b32_e32 v8, v7, v10
	v_lshlrev_b32_e32 v8, 2, v8
	global_load_dword v132, v8, s[24:25]
.LccE2:
	v_lshlrev_b32_e32 v137, 1, v6
	s_add_u32 s20, s20, 0x200
	s_sub_u32 s21, s20, 0x380
	s_lshl_b32 s21, s21, 8
	v_add_u32_e32 v6, s21, v1
	s_cmpk_lt_u32 s20, 0x480
	s_cbranch_scc1 .LccA3
	s_cmpk_lt_u32 s20, 0x580
	s_cbranch_scc1 .LccB3
	s_cmpk_lt_u32 s20, 0x980
	s_cbranch_scc1 .LccC3
	v_add_u32_e32 v6, 0xfffa0000, v6
	v_and_b32_e32 v7, 0xff, v6
	v_bfe_u32 v8, v6, 8, 7
	v_bfe_u32 v9, v6, 15, 2
	v_lshl_or_b32 v8, v7, 9, v8
	v_lshl_or_b32 v8, v9, 7, v8
	v_and_b32_e32 v10, 0xfffe0000, v6
	v_or_b32_e32 v8, v8, v10
	v_lshlrev_b32_e32 v8, 2, v8
	global_load_dword v133, v8, s[30:31]
	s_branch .LccE3
.LccC3:
	v_add_u32_e32 v6, 0xfffe0000, v6
	v_and_b32_e32 v7, 0x7f, v6
	v_bfe_u32 v8, v6, 7, 8
	v_bfe_u32 v9, v6, 15, 2
	v_lshl_or_b32 v7, v8, 9, v7
	v_lshl_or_b32 v7, v9, 7, v7
	v_and_b32_e32 v10, 0xfffe0000, v6
	v_or_b32_e32 v8, v7, v10
	v_lshlrev_b32_e32 v8, 2, v8
	global_load_dword v133, v8, s[28:29]
	s_branch .LccE3
.LccB3:
	v_add_u32_e32 v6, 0xffff0000, v6
	v_and_b32_e32 v7, 0xff, v6
	v_bfe_u32 v8, v6, 8, 6
	v_bfe_u32 v9, v6, 14, 1
	v_lshl_or_b32 v8, v7, 7, v8
	v_lshl_or_b32 v8, v9, 6, v8
	v_and_b32_e32 v10, 0xffff8000, v6
	v_or_b32_e32 v8, v8, v10
	v_lshlrev_b32_e32 v8, 2, v8
	global_load_dword v133, v8, s[26:27]
	s_branch .LccE3
.LccA3:
	v_and_b32_e32 v7, 63, v6
	v_bfe_u32 v8, v6, 6, 8
	v_bfe_u32 v9, v6, 14, 1
	v_lshl_or_b32 v7, v8, 7, v7
	v_lshl_or_b32 v7, v9, 6, v7
	v_and_b32_e32 v10, 0xffff8000, v6
	v_or_b32_e32 v8, v7, v10
	v_lshlrev_b32_e32 v8, 2, v8
	global_load_dword v133, v8, s[24:25]
.LccE3:
	v_lshlrev_b32_e32 v138, 1, v6
	s_add_u32 s20, s20, 0x200
	s_sub_u32 s21, s20, 0x380
	s_lshl_b32 s21, s21, 8
	v_add_u32_e32 v6, s21, v1
	s_cmpk_lt_u32 s20, 0x480
	s_cbranch_scc1 .LccA4
	s_cmpk_lt_u32 s20, 0x580
	s_cbranch_scc1 .LccB4
	s_cmpk_lt_u32 s20, 0x980
	s_cbranch_scc1 .LccC4
	v_add_u32_e32 v6, 0xfffa0000, v6
	v_and_b32_e32 v7, 0xff, v6
	v_bfe_u32 v8, v6, 8, 7
	v_bfe_u32 v9, v6, 15, 2
	v_lshl_or_b32 v8, v7, 9, v8
	v_lshl_or_b32 v8, v9, 7, v8
	v_and_b32_e32 v10, 0xfffe0000, v6
	v_or_b32_e32 v8, v8, v10
	v_lshlrev_b32_e32 v8, 2, v8
	global_load_dword v134, v8, s[30:31]
	s_branch .LccE4
.LccC4:
	v_add_u32_e32 v6, 0xfffe0000, v6
	v_and_b32_e32 v7, 0x7f, v6
	v_bfe_u32 v8, v6, 7, 8
	v_bfe_u32 v9, v6, 15, 2
	v_lshl_or_b32 v7, v8, 9, v7
	v_lshl_or_b32 v7, v9, 7, v7
	v_and_b32_e32 v10, 0xfffe0000, v6
	v_or_b32_e32 v8, v7, v10
	v_lshlrev_b32_e32 v8, 2, v8
	global_load_dword v134, v8, s[28:29]
	s_branch .LccE4
.LccB4:
	v_add_u32_e32 v6, 0xffff0000, v6
	v_and_b32_e32 v7, 0xff, v6
	v_bfe_u32 v8, v6, 8, 6
	v_bfe_u32 v9, v6, 14, 1
	v_lshl_or_b32 v8, v7, 7, v8
	v_lshl_or_b32 v8, v9, 6, v8
	v_and_b32_e32 v10, 0xffff8000, v6
	v_or_b32_e32 v8, v8, v10
	v_lshlrev_b32_e32 v8, 2, v8
	global_load_dword v134, v8, s[26:27]
	s_branch .LccE4
.LccA4:
	v_and_b32_e32 v7, 63, v6
	v_bfe_u32 v8, v6, 6, 8
	v_bfe_u32 v9, v6, 14, 1
	v_lshl_or_b32 v7, v8, 7, v7
	v_lshl_or_b32 v7, v9, 6, v7
	v_and_b32_e32 v10, 0xffff8000, v6
	v_or_b32_e32 v8, v7, v10
	v_lshlrev_b32_e32 v8, 2, v8
	global_load_dword v134, v8, s[24:25]
.LccE4:
	v_lshlrev_b32_e32 v139, 1, v6
	s_add_u32 s20, s20, 0x200
.Lcc_skip:
	s_mov_b32 s12, s2

.Lwc_sel:
	s_lshl_b32 s19, s14, 6
	s_mul_i32 s19, s19, s15
	s_lshl_b32 s20, s18, 9
	s_add_u32 s19, s19, s20
	s_add_u32 s16, s16, s19
	s_addc_u32 s17, s17, 0
	s_lshl_b32 s20, s15, 3
	v_mul_lo_u32 v5, v4, s20
	v_add_u32_e32 v5, v5, v3
	global_load_dwordx4 v[8:11], v5, s[16:17]
	s_add_u32 s16, s16, s15
	s_addc_u32 s17, s17, 0
	global_load_dwordx4 v[12:15], v5, s[16:17]
	s_add_u32 s16, s16, s15
	s_addc_u32 s17, s17, 0
	global_load_dwordx4 v[16:19], v5, s[16:17]
	s_add_u32 s16, s16, s15
	s_addc_u32 s17, s17, 0
	global_load_dwordx4 v[20:23], v5, s[16:17]
	s_add_u32 s16, s16, s15
	s_addc_u32 s17, s17, 0
	global_load_dwordx4 v[24:27], v5, s[16:17]
	s_add_u32 s16, s16, s15
	s_addc_u32 s17, s17, 0
	global_load_dwordx4 v[28:31], v5, s[16:17]
	s_add_u32 s16, s16, s15
	s_addc_u32 s17, s17, 0
	global_load_dwordx4 v[32:35], v5, s[16:17]
	s_add_u32 s16, s16, s15
	s_addc_u32 s17, s17, 0
	global_load_dwordx4 v[36:39], v5, s[16:17]
	s_lshl_b32 s19, s12, 14
	s_add_u32 s20, s100, s19
	s_addc_u32 s21, s101, 0
	s_waitcnt vmcnt(0)
	v_cvt_pk_bf16_f32 v40, v8, v12
	v_cvt_pk_bf16_f32 v41, v16, v20
	v_cvt_pk_bf16_f32 v42, v24, v28
	v_cvt_pk_bf16_f32 v43, v32, v36
	global_store_dwordx4 v2, v[40:43], s[20:21]
	v_cvt_pk_bf16_f32 v44, v9, v13
	v_cvt_pk_bf16_f32 v45, v17, v21
	v_cvt_pk_bf16_f32 v46, v25, v29
	v_cvt_pk_bf16_f32 v47, v33, v37
	global_store_dwordx4 v2, v[44:47], s[20:21] offset:1024
	v_cvt_pk_bf16_f32 v48, v10, v14
	v_cvt_pk_bf16_f32 v49, v18, v22
	v_cvt_pk_bf16_f32 v50, v26, v30
	v_cvt_pk_bf16_f32 v51, v34, v38
	global_store_dwordx4 v2, v[48:51], s[20:21] offset:2048
	v_cvt_pk_bf16_f32 v52, v11, v15
	v_cvt_pk_bf16_f32 v53, v19, v23
	v_cvt_pk_bf16_f32 v54, v27, v31
	v_cvt_pk_bf16_f32 v55, v35, v39
	global_store_dwordx4 v2, v[52:55], s[20:21] offset:3072
	s_cmp_lg_u32 s3, 0x200
	s_cbranch_scc1 .Lwc_gen
	s_add_u32 s12, s12, 0x100
	s_cmpk_lt_u32 s12, 0x200
	s_cbranch_scc1 .Lwc_done
	s_branch .Lwc_loop
.Lwc_gen:
	s_add_u32 s12, s12, s3
	s_branch .Lwc_loop

.LBB0_33:
	s_andn2_b64 vcc, exec, s[2:3]
	s_cbranch_vccnz .LBB0_47
	v_readlane_b32 s98, v255, 46
	s_nop 1
	s_cmp_lg_u32 s98, 0
	s_cbranch_scc1 .LBB0_47
	s_lshl_b32 s2, s14, 8
	s_add_i32 s2, s2, 0xfffc8000
	v_add_u32_e32 v4, s2, v2
	s_mov_b32 s2, 0xffff
	v_cmp_lt_i32_e32 vcc, s2, v4
	s_and_saveexec_b64 s[2:3], vcc
	s_xor_b64 s[2:3], exec, s[2:3]
	s_cbranch_execz .LBB0_44
	s_mov_b32 s4, 0x1ffff
	v_cmp_lt_u32_e32 vcc, s4, v4
	s_and_saveexec_b64 s[4:5], vcc
	s_xor_b64 s[4:5], exec, s[4:5]
	s_cbranch_execz .LBB0_41
	s_mov_b32 s6, 0x5ffff
	v_cmp_lt_u32_e32 vcc, s6, v4
	s_and_saveexec_b64 s[6:7], vcc
	s_xor_b64 s[6:7], exec, s[6:7]
	s_cbranch_execz .LBB0_38
	s_load_dwordx16 s[16:31], s[0:1], 0x0
	v_add_u32_e32 v6, 0xfffa0000, v4
	v_lshlrev_b32_e32 v0, 9, v2
	v_and_b32_e32 v0, 0x1fe00, v0
	v_and_b32_e32 v3, 0xfffe0000, v6
	v_bfe_u32 v4, v4, 8, 9
	v_or3_b32 v0, v3, v0, v4
	s_waitcnt lgkmcnt(0)
	v_lshl_add_u64 v[4:5], v[0:1], 2, s[28:29]
	global_load_dword v0, v[4:5], off
	v_mov_b32_e32 v7, v1
	v_lshl_add_u64 v[4:5], v[6:7], 1, s[70:71]
	s_waitcnt vmcnt(0)
	v_cvt_pk_bf16_f32 v0, v0, s0
	global_store_short v[4:5], v0, off

.LBB0_66:
	v_readlane_b32 s98, v255, 46
	s_nop 1
	s_cmp_eq_u32 s98, 0
	s_cbranch_scc1 .Lcs_skip
	s_movk_i32 s2, 0x200
	s_cmpk_lt_u32 s55, 0x180
	s_cselect_b32 s2, 0x400, s2
	s_add_u32 s2, s2, s55
	s_waitcnt vmcnt(0)
	s_movk_i32 s3, 0x150
	s_cmpk_lt_u32 s2, 0x980
	s_cselect_b32 s3, 0x148, s3
	s_cmpk_lt_u32 s2, 0x580
	s_cselect_b32 s3, 0x140, s3
	s_cmpk_lt_u32 s2, 0x480
	s_cselect_b32 s3, 0x138, s3
	v_readlane_b32 s4, v253, 4
	v_readlane_b32 s5, v253, 5
	s_nop 1
	s_sub_u32 s4, s4, 0x228
	s_subb_u32 s5, s5, 0
	s_add_u32 s4, s4, s3
	s_addc_u32 s5, s5, 0
	s_load_dwordx2 s[4:5], s[4:5], 0x0
	v_cvt_pk_bf16_f32 v130, v130, v130
	s_waitcnt lgkmcnt(0)
	global_store_short v135, v130, s[4:5]
	s_add_u32 s2, s2, 0x200
	s_movk_i32 s3, 0x150
	s_cmpk_lt_u32 s2, 0x980
	s_cselect_b32 s3, 0x148, s3
	s_cmpk_lt_u32 s2, 0x580
	s_cselect_b32 s3, 0x140, s3
	s_cmpk_lt_u32 s2, 0x480
	s_cselect_b32 s3, 0x138, s3
	v_readlane_b32 s4, v253, 4
	v_readlane_b32 s5, v253, 5
	s_nop 1
	s_sub_u32 s4, s4, 0x228
	s_subb_u32 s5, s5, 0
	s_add_u32 s4, s4, s3
	s_addc_u32 s5, s5, 0
	s_load_dwordx2 s[4:5], s[4:5], 0x0
	v_cvt_pk_bf16_f32 v131, v131, v131
	s_waitcnt lgkmcnt(0)
	global_store_short v136, v131, s[4:5]
	s_add_u32 s2, s2, 0x200
	s_movk_i32 s3, 0x150
	s_cmpk_lt_u32 s2, 0x980
	s_cselect_b32 s3, 0x148, s3
	s_cmpk_lt_u32 s2, 0x580
	s_cselect_b32 s3, 0x140, s3
	s_cmpk_lt_u32 s2, 0x480
	s_cselect_b32 s3, 0x138, s3
	v_readlane_b32 s4, v253, 4
	v_readlane_b32 s5, v253, 5
	s_nop 1
	s_sub_u32 s4, s4, 0x228
	s_subb_u32 s5, s5, 0
	s_add_u32 s4, s4, s3
	s_addc_u32 s5, s5, 0
	s_load_dwordx2 s[4:5], s[4:5], 0x0
	v_cvt_pk_bf16_f32 v132, v132, v132
	s_waitcnt lgkmcnt(0)
	global_store_short v137, v132, s[4:5]
	s_add_u32 s2, s2, 0x200
	s_movk_i32 s3, 0x150
	s_cmpk_lt_u32 s2, 0x980
	s_cselect_b32 s3, 0x148, s3
	s_cmpk_lt_u32 s2, 0x580
	s_cselect_b32 s3, 0x140, s3
	s_cmpk_lt_u32 s2, 0x480
	s_cselect_b32 s3, 0x138, s3
	v_readlane_b32 s4, v253, 4
	v_readlane_b32 s5, v253, 5
	s_nop 1
	s_sub_u32 s4, s4, 0x228
	s_subb_u32 s5, s5, 0
	s_add_u32 s4, s4, s3
	s_addc_u32 s5, s5, 0
	s_load_dwordx2 s[4:5], s[4:5], 0x0
	v_cvt_pk_bf16_f32 v133, v133, v133
	s_waitcnt lgkmcnt(0)
	global_store_short v138, v133, s[4:5]
	s_add_u32 s2, s2, 0x200
	s_movk_i32 s3, 0x150
	s_cmpk_lt_u32 s2, 0x980
	s_cselect_b32 s3, 0x148, s3
	s_cmpk_lt_u32 s2, 0x580
	s_cselect_b32 s3, 0x140, s3
	s_cmpk_lt_u32 s2, 0x480
	s_cselect_b32 s3, 0x138, s3
	v_readlane_b32 s4, v253, 4
	v_readlane_b32 s5, v253, 5
	s_nop 1
	s_sub_u32 s4, s4, 0x228
	s_subb_u32 s5, s5, 0
	s_add_u32 s4, s4, s3
	s_addc_u32 s5, s5, 0
	s_load_dwordx2 s[4:5], s[4:5], 0x0
	v_cvt_pk_bf16_f32 v134, v134, v134
	s_waitcnt lgkmcnt(0)
	global_store_short v139, v134, s[4:5]
	s_add_u32 s2, s2, 0x200
